# NORM/NORMKV per-row wave_sum: the four ds_swizzle SWAP1/2/4/8 + lgkm waits replaced by DPP adds (quad_perm, row_half_mirror, row_mirror)
# baseline (speedup 1.0000x reference)
.Lmy_nk_noreload:
	v_cvt_f32_f16_sdwa v43, v32 dst_sel:DWORD dst_unused:UNUSED_PAD src0_sel:WORD_1
	v_cvt_f32_f16_e32 v42, v32
	v_cvt_f32_f16_sdwa v41, v33 dst_sel:DWORD dst_unused:UNUSED_PAD src0_sel:WORD_1
	v_cvt_f32_f16_e32 v40, v33
	v_cvt_f32_f16_sdwa v45, v30 dst_sel:DWORD dst_unused:UNUSED_PAD src0_sel:WORD_1
	v_cvt_f32_f16_e32 v44, v30
	v_cvt_f32_f16_sdwa v47, v31 dst_sel:DWORD dst_unused:UNUSED_PAD src0_sel:WORD_1
	v_cvt_f32_f16_e32 v46, v31
	v_cvt_f32_f16_sdwa v37, v26 dst_sel:DWORD dst_unused:UNUSED_PAD src0_sel:WORD_1
	v_cvt_f32_f16_e32 v36, v26
	v_pk_mul_f32 v[32:33], v[42:43], v[42:43]
	v_pk_mul_f32 v[34:35], v[40:41], v[40:41]
	v_pk_mul_f32 v[48:49], v[44:45], v[44:45]
	v_pk_mul_f32 v[50:51], v[46:47], v[46:47]
	v_pk_mul_f32 v[52:53], v[36:37], v[36:37]
	v_add_f32_e32 v50, v50, v51
	v_add_f32_e32 v48, v48, v49
	v_add_f32_e32 v34, v34, v35
	v_add_f32_e32 v32, v32, v33
	v_add_f32_e32 v48, v48, v50
	v_add_f32_e32 v32, v32, v34
	v_add_f32_e32 v34, v52, v53
	v_cvt_f32_f16_sdwa v39, v27 dst_sel:DWORD dst_unused:UNUSED_PAD src0_sel:WORD_1
	v_cvt_f32_f16_e32 v38, v27
	v_cvt_f32_f16_sdwa v27, v28 dst_sel:DWORD dst_unused:UNUSED_PAD src0_sel:WORD_1
	v_cvt_f32_f16_e32 v26, v28
	v_cvt_f32_f16_sdwa v31, v29 dst_sel:DWORD dst_unused:UNUSED_PAD src0_sel:WORD_1
	v_cvt_f32_f16_e32 v30, v29
	v_pk_mul_f32 v[54:55], v[38:39], v[38:39]
	v_pk_mul_f32 v[28:29], v[26:27], v[26:27]
	v_add_f32_e32 v33, v54, v55
	v_pk_mul_f32 v[58:59], v[30:31], v[30:31]
	v_add_f32_e32 v32, v32, v48
	v_add_f32_e32 v33, v34, v33
	v_add_f32_e32 v32, v33, v32
	v_add_f32_e32 v33, v58, v59
	v_add_f32_e32 v28, v28, v29
	v_add_f32_e32 v28, v28, v33
	v_add_f32_e32 v28, v28, v32
	s_ashr_i32 s2, s50, 13
	v_mad_i64_i32 v[48:49], s[0:1], s2, v252, v[8:9]
	v_lshl_add_u64 v[34:35], s[52:53], 0, v[0:1]
	s_waitcnt lgkmcnt(0)
	s_nop 1
	v_add_f32_dpp v28, v28, v28 quad_perm:[1,0,3,2] row_mask:0xf bank_mask:0xf
	s_ashr_i32 s3, s2, 31
	s_waitcnt lgkmcnt(0)
	s_nop 1
	v_add_f32_dpp v28, v28, v28 quad_perm:[2,3,0,1] row_mask:0xf bank_mask:0xf
	s_waitcnt lgkmcnt(0)
	s_nop 1
	v_add_f32_dpp v28, v28, v28 row_half_mirror row_mask:0xf bank_mask:0xf
	s_waitcnt lgkmcnt(0)
	s_nop 1
	v_add_f32_dpp v28, v28, v28 row_mirror row_mask:0xf bank_mask:0xf
	v_mov_b32_e32 v29, v28
	s_nop 1
	v_permlane16_swap_b32_e32 v29, v28
	s_waitcnt lgkmcnt(0)
	v_add_f32_e32 v28, v28, v29
	v_mov_b32_e32 v29, v28
	s_nop 1
	v_permlane32_swap_b32_e32 v28, v29
	v_add_f32_e32 v28, v28, v29
	v_fmamk_f32 v28, v28, 0x3a800000, v244
	v_rsq_f32_e32 v32, v28
	v_mad_i64_i32 v[28:29], s[0:1], s2, v252, v[2:3]
	s_mov_b32 s0, 0x1b400000
	v_pk_mul_f32 v[40:41], v[40:41], v[32:33] op_sel_hi:[1,0]
	v_pk_mul_f32 v[42:43], v[42:43], v[32:33] op_sel_hi:[1,0]
	v_pk_mul_f32 v[46:47], v[46:47], v[32:33] op_sel_hi:[1,0]
	v_pk_mul_f32 v[44:45], v[44:45], v[32:33] op_sel_hi:[1,0]
	v_pk_mul_f32 v[38:39], v[38:39], v[32:33] op_sel_hi:[1,0]
	v_pk_mul_f32 v[36:37], v[36:37], v[32:33] op_sel_hi:[1,0]
	v_mov_b64_e32 v[50:51], v[100:101]
	v_mov_b64_e32 v[52:53], v[102:103]
	v_pk_mul_f32 v[54:55], v[50:51], v[42:43]
	v_pk_mul_f32 v[58:59], v[52:53], v[40:41]
	v_mov_b64_e32 v[50:51], v[104:105]
	v_mov_b64_e32 v[52:53], v[106:107]
	v_pk_add_f32 v[60:61], v[52:53], 1.0 op_sel_hi:[1,0]
	v_pk_add_f32 v[62:63], v[50:51], 1.0 op_sel_hi:[1,0]
	v_mov_b64_e32 v[50:51], v[108:109]
	v_mov_b64_e32 v[52:53], v[110:111]
	v_pk_fma_f32 v[50:51], v[62:63], v[54:55], v[50:51]
	v_add_co_u32_e32 v54, vcc, s0, v34
	v_pk_fma_f32 v[52:53], v[60:61], v[58:59], v[52:53]
	s_nop 0
	v_addc_co_u32_e32 v55, vcc, 0, v35, vcc
	v_cvt_pk_bf16_f32 v50, v50, v51
	v_cvt_pk_bf16_f32 v51, v52, v53
	global_store_dwordx2 v[54:55], v[50:51], off
	v_mov_b64_e32 v[50:51], v[112:113]
	v_mov_b64_e32 v[52:53], v[114:115]
	s_lshl_b64 s[0:1], s[2:3], 13
	v_pk_mul_f32 v[58:59], v[50:51], v[44:45]
	v_pk_mul_f32 v[60:61], v[52:53], v[46:47]
	v_mov_b64_e32 v[50:51], v[116:117]
	v_mov_b64_e32 v[52:53], v[118:119]
	v_pk_add_f32 v[62:63], v[52:53], 1.0 op_sel_hi:[1,0]
	v_pk_add_f32 v[64:65], v[50:51], 1.0 op_sel_hi:[1,0]
	v_mov_b64_e32 v[50:51], v[120:121]
	v_mov_b64_e32 v[52:53], v[122:123]
	v_pk_fma_f32 v[50:51], v[64:65], v[58:59], v[50:51]
	v_pk_fma_f32 v[52:53], v[62:63], v[60:61], v[52:53]
	v_cvt_pk_bf16_f32 v50, v50, v51
	s_nop 0
	v_cvt_pk_bf16_f32 v51, v52, v53
	global_store_dwordx2 v[54:55], v[50:51], off offset:512
	v_mov_b64_e32 v[50:51], v[124:125]
	v_mov_b64_e32 v[52:53], v[126:127]
	v_pk_mul_f32 v[58:59], v[36:37], v[50:51]
	v_pk_mul_f32 v[60:61], v[38:39], v[52:53]
	v_mov_b64_e32 v[50:51], v[128:129]
	v_mov_b64_e32 v[52:53], v[130:131]
	v_pk_add_f32 v[62:63], v[52:53], 1.0 op_sel_hi:[1,0]
	v_pk_add_f32 v[64:65], v[50:51], 1.0 op_sel_hi:[1,0]
	v_mov_b64_e32 v[50:51], v[132:133]
	v_mov_b64_e32 v[52:53], v[134:135]
	v_pk_fma_f32 v[50:51], v[58:59], v[64:65], v[50:51]
	v_pk_fma_f32 v[52:53], v[60:61], v[62:63], v[52:53]
	v_cvt_pk_bf16_f32 v50, v50, v51
	s_nop 0
	v_cvt_pk_bf16_f32 v51, v52, v53
	global_store_dwordx2 v[54:55], v[50:51], off offset:1024
	v_pk_mul_f32 v[50:51], v[30:31], v[32:33] op_sel_hi:[1,0]
	v_pk_mul_f32 v[52:53], v[26:27], v[32:33] op_sel_hi:[1,0]
	v_mov_b64_e32 v[30:31], v[136:137]
	v_mov_b64_e32 v[32:33], v[138:139]
	v_pk_mul_f32 v[58:59], v[52:53], v[30:31]
	v_pk_mul_f32 v[60:61], v[50:51], v[32:33]
	v_mov_b64_e32 v[30:31], v[140:141]
	v_mov_b64_e32 v[32:33], v[142:143]
	s_nop 0
	v_mov_b64_e32 v[26:27], v[144:145]
	v_mov_b64_e32 v[28:29], v[146:147]
	v_lshl_add_u64 v[48:49], v[4:5], 0, s[0:1]
	v_pk_add_f32 v[30:31], v[30:31], 1.0 op_sel_hi:[1,0]
	v_pk_add_f32 v[32:33], v[32:33], 1.0 op_sel_hi:[1,0]
	v_pk_fma_f32 v[26:27], v[58:59], v[30:31], v[26:27]
	v_pk_fma_f32 v[28:29], v[60:61], v[32:33], v[28:29]
	v_cvt_pk_bf16_f32 v26, v26, v27
	s_nop 0
	v_cvt_pk_bf16_f32 v27, v28, v29
	global_store_dwordx2 v[54:55], v[26:27], off offset:1536
	v_mov_b64_e32 v[26:27], v[148:149]
	v_mov_b64_e32 v[28:29], v[150:151]
	v_lshl_add_u64 v[54:55], v[10:11], 0, s[0:1]
	s_mov_b32 s0, 0x3400000
	v_pk_mul_f32 v[32:33], v[42:43], v[26:27]
	v_pk_mul_f32 v[40:41], v[40:41], v[28:29]
	v_mov_b64_e32 v[26:27], v[152:153]
	v_mov_b64_e32 v[28:29], v[154:155]
	v_pk_add_f32 v[42:43], v[28:29], 1.0 op_sel_hi:[1,0]
	v_mov_b64_e32 v[28:29], v[156:157]
	v_mov_b64_e32 v[30:31], v[158:159]
	v_pk_add_f32 v[58:59], v[26:27], 1.0 op_sel_hi:[1,0]
	v_pk_fma_f32 v[26:27], v[40:41], v[42:43], v[30:31]
	v_pk_fma_f32 v[28:29], v[32:33], v[58:59], v[28:29]
	v_add_co_u32_e32 v58, vcc, s0, v34
	v_cvt_pk_bf16_f32 v30, v28, v29
	v_cvt_pk_bf16_f32 v31, v26, v27
	s_nop 1
	v_addc_co_u32_e32 v59, vcc, 0, v35, vcc
	global_store_dwordx2 v[58:59], v[30:31], off
	v_mov_b64_e32 v[30:31], v[160:161]
	v_mov_b64_e32 v[32:33], v[162:163]
	v_pk_mul_f32 v[40:41], v[44:45], v[30:31]
	v_pk_mul_f32 v[42:43], v[46:47], v[32:33]
	v_mov_b64_e32 v[30:31], v[164:165]
	v_mov_b64_e32 v[32:33], v[166:167]
	v_pk_add_f32 v[44:45], v[32:33], 1.0 op_sel_hi:[1,0]
	v_mov_b64_e32 v[32:33], v[168:169]
	v_mov_b64_e32 v[34:35], v[170:171]
	v_pk_add_f32 v[46:47], v[30:31], 1.0 op_sel_hi:[1,0]
	v_pk_fma_f32 v[30:31], v[42:43], v[44:45], v[34:35]
	v_pk_fma_f32 v[32:33], v[40:41], v[46:47], v[32:33]
	s_nop 0
	v_cvt_pk_bf16_f32 v34, v32, v33
	v_cvt_pk_bf16_f32 v35, v30, v31
	global_store_dwordx2 v[58:59], v[34:35], off offset:512
	v_mov_b64_e32 v[40:41], v[172:173]
	v_mov_b64_e32 v[42:43], v[174:175]
	v_pk_mul_f32 v[40:41], v[36:37], v[40:41]
	v_mov_b64_e32 v[34:35], v[176:177]
	v_mov_b64_e32 v[36:37], v[178:179]
	v_pk_mul_f32 v[38:39], v[38:39], v[42:43]
	v_pk_add_f32 v[42:43], v[36:37], 1.0 op_sel_hi:[1,0]
	v_pk_add_f32 v[44:45], v[34:35], 1.0 op_sel_hi:[1,0]
	v_mov_b64_e32 v[34:35], v[180:181]
	v_mov_b64_e32 v[36:37], v[182:183]
	v_pk_fma_f32 v[38:39], v[38:39], v[42:43], v[36:37]
	v_pk_fma_f32 v[40:41], v[40:41], v[44:45], v[34:35]
	s_nop 0
	v_cvt_pk_bf16_f32 v34, v40, v41
	v_cvt_pk_bf16_f32 v35, v38, v39
	global_store_dwordx2 v[58:59], v[34:35], off offset:1024
	v_mov_b64_e32 v[34:35], v[184:185]
	v_mov_b64_e32 v[36:37], v[186:187]
	v_pk_mul_f32 v[46:47], v[52:53], v[34:35]
	v_pk_mul_f32 v[50:51], v[50:51], v[36:37]
	v_mov_b64_e32 v[34:35], v[188:189]
	v_mov_b64_e32 v[36:37], v[190:191]
	v_mov_b64_e32 v[42:43], v[192:193]
	v_mov_b64_e32 v[44:45], v[194:195]
	v_pk_add_f32 v[36:37], v[36:37], 1.0 op_sel_hi:[1,0]
	v_pk_add_f32 v[52:53], v[34:35], 1.0 op_sel_hi:[1,0]
	v_pk_fma_f32 v[34:35], v[50:51], v[36:37], v[44:45]
	v_pk_fma_f32 v[36:37], v[46:47], v[52:53], v[42:43]
	s_nop 0
	v_cvt_pk_bf16_f32 v42, v36, v37
	v_cvt_pk_bf16_f32 v43, v34, v35
	global_store_dwordx2 v[58:59], v[42:43], off offset:1536
	v_mbcnt_lo_u32_b32 v96, -1, 0
	v_mbcnt_hi_u32_b32 v96, -1, v96
	ds_read_b128 v[196:199], v56
	ds_read_b128 v[200:203], v56 offset:1024
	ds_read_b128 v[204:207], v56 offset:2048
	ds_read_b128 v[208:211], v56 offset:3072
	ds_read_b128 v[212:215], v56 offset:4096
	ds_read_b128 v[216:219], v56 offset:5120
	ds_read_b128 v[220:223], v56 offset:6144
	ds_read_b128 v[224:227], v56 offset:7168
	v_lshrrev_b32_e32 v97, 2, v96
	v_and_b32_e32 v98, 3, v96
	v_lshl_or_b32 v97, v97, 4, v98
	v_and_b32_e32 v97, 63, v97
	v_lshlrev_b32_e32 v97, 2, v97
	s_waitcnt lgkmcnt(4)
	v_mul_f32_e32 v228, v29, v197
	v_mul_f32_e32 v229, v27, v199
	v_mul_f32_e32 v230, v33, v201
	v_mul_f32_e32 v231, v31, v203
	v_mul_f32_e32 v232, v41, v205
	v_mul_f32_e32 v233, v39, v207
	v_mul_f32_e32 v234, v37, v209
	v_mul_f32_e32 v235, v35, v211
	v_fmac_f32_e32 v228, v28, v196
	v_fmac_f32_e32 v229, v26, v198
	v_fmac_f32_e32 v230, v32, v200
	v_fmac_f32_e32 v231, v30, v202
	v_fmac_f32_e32 v232, v40, v204
	v_fmac_f32_e32 v233, v38, v206
	v_fmac_f32_e32 v234, v36, v208
	v_fmac_f32_e32 v235, v34, v210
	v_add_f32_e32 v228, v228, v229
	v_add_f32_e32 v230, v230, v231
	v_add_f32_e32 v232, v232, v233
	v_add_f32_e32 v234, v234, v235
	v_add_f32_e32 v80, 0, v228
	v_add_f32_e32 v80, v80, v230
	v_add_f32_e32 v80, v80, v232
	v_add_f32_e32 v80, v80, v234
	ds_read_b128 v[196:199], v56 offset:8192
	ds_read_b128 v[200:203], v56 offset:9216
	ds_read_b128 v[204:207], v56 offset:10240
	ds_read_b128 v[208:211], v56 offset:11264
	s_waitcnt lgkmcnt(4)
	v_mul_f32_e32 v228, v29, v213
	v_mul_f32_e32 v229, v27, v215
	v_mul_f32_e32 v230, v33, v217
	v_mul_f32_e32 v231, v31, v219
	v_mul_f32_e32 v232, v41, v221
	v_mul_f32_e32 v233, v39, v223
	v_mul_f32_e32 v234, v37, v225
	v_mul_f32_e32 v235, v35, v227
	v_fmac_f32_e32 v228, v28, v212
	v_fmac_f32_e32 v229, v26, v214
	v_fmac_f32_e32 v230, v32, v216
	v_fmac_f32_e32 v231, v30, v218
	v_fmac_f32_e32 v232, v40, v220
	v_fmac_f32_e32 v233, v38, v222
	v_fmac_f32_e32 v234, v36, v224
	v_fmac_f32_e32 v235, v34, v226
	v_add_f32_e32 v228, v228, v229
	v_add_f32_e32 v230, v230, v231
	v_add_f32_e32 v232, v232, v233
	v_add_f32_e32 v234, v234, v235
	v_add_f32_e32 v81, 0, v228
	v_add_f32_e32 v81, v81, v230
	v_add_f32_e32 v81, v81, v232
	v_add_f32_e32 v81, v81, v234
	ds_read_b128 v[212:215], v56 offset:12288
	ds_read_b128 v[216:219], v56 offset:13312
	ds_read_b128 v[220:223], v56 offset:14336
	ds_read_b128 v[224:227], v56 offset:15360
	s_waitcnt lgkmcnt(4)
	v_mul_f32_e32 v228, v29, v197
	v_mul_f32_e32 v229, v27, v199
	v_mul_f32_e32 v230, v33, v201
	v_mul_f32_e32 v231, v31, v203
	v_mul_f32_e32 v232, v41, v205
	v_mul_f32_e32 v233, v39, v207
	v_mul_f32_e32 v234, v37, v209
	v_mul_f32_e32 v235, v35, v211
	v_fmac_f32_e32 v228, v28, v196
	v_fmac_f32_e32 v229, v26, v198
	v_fmac_f32_e32 v230, v32, v200
	v_fmac_f32_e32 v231, v30, v202
	v_fmac_f32_e32 v232, v40, v204
	v_fmac_f32_e32 v233, v38, v206
	v_fmac_f32_e32 v234, v36, v208
	v_fmac_f32_e32 v235, v34, v210
	v_add_f32_e32 v228, v228, v229
	v_add_f32_e32 v230, v230, v231
	v_add_f32_e32 v232, v232, v233
	v_add_f32_e32 v234, v234, v235
	v_add_f32_e32 v82, 0, v228
	v_add_f32_e32 v82, v82, v230
	v_add_f32_e32 v82, v82, v232
	v_add_f32_e32 v82, v82, v234
	ds_read_b128 v[196:199], v56 offset:16384
	ds_read_b128 v[200:203], v56 offset:17408
	ds_read_b128 v[204:207], v56 offset:18432
	ds_read_b128 v[208:211], v56 offset:19456
	s_waitcnt lgkmcnt(4)
	v_mul_f32_e32 v228, v29, v213
	v_mul_f32_e32 v229, v27, v215
	v_mul_f32_e32 v230, v33, v217
	v_mul_f32_e32 v231, v31, v219
	v_mul_f32_e32 v232, v41, v221
	v_mul_f32_e32 v233, v39, v223
	v_mul_f32_e32 v234, v37, v225
	v_mul_f32_e32 v235, v35, v227
	v_fmac_f32_e32 v228, v28, v212
	v_fmac_f32_e32 v229, v26, v214
	v_fmac_f32_e32 v230, v32, v216
	v_fmac_f32_e32 v231, v30, v218
	v_fmac_f32_e32 v232, v40, v220
	v_fmac_f32_e32 v233, v38, v222
	v_fmac_f32_e32 v234, v36, v224
	v_fmac_f32_e32 v235, v34, v226
	v_add_f32_e32 v228, v228, v229
	v_add_f32_e32 v230, v230, v231
	v_add_f32_e32 v232, v232, v233
	v_add_f32_e32 v234, v234, v235
	v_add_f32_e32 v83, 0, v228
	v_add_f32_e32 v83, v83, v230
	v_add_f32_e32 v83, v83, v232
	v_add_f32_e32 v83, v83, v234
	ds_read_b128 v[212:215], v56 offset:20480
	ds_read_b128 v[216:219], v56 offset:21504
	ds_read_b128 v[220:223], v56 offset:22528
	ds_read_b128 v[224:227], v56 offset:23552
	s_waitcnt lgkmcnt(4)
	v_mul_f32_e32 v228, v29, v197
	v_mul_f32_e32 v229, v27, v199
	v_mul_f32_e32 v230, v33, v201
	v_mul_f32_e32 v231, v31, v203
	v_mul_f32_e32 v232, v41, v205
	v_mul_f32_e32 v233, v39, v207
	v_mul_f32_e32 v234, v37, v209
	v_mul_f32_e32 v235, v35, v211
	v_fmac_f32_e32 v228, v28, v196
	v_fmac_f32_e32 v229, v26, v198
	v_fmac_f32_e32 v230, v32, v200
	v_fmac_f32_e32 v231, v30, v202
	v_fmac_f32_e32 v232, v40, v204
	v_fmac_f32_e32 v233, v38, v206
	v_fmac_f32_e32 v234, v36, v208
	v_fmac_f32_e32 v235, v34, v210
	v_add_f32_e32 v228, v228, v229
	v_add_f32_e32 v230, v230, v231
	v_add_f32_e32 v232, v232, v233
	v_add_f32_e32 v234, v234, v235
	v_add_f32_e32 v84, 0, v228
	v_add_f32_e32 v84, v84, v230
	v_add_f32_e32 v84, v84, v232
	v_add_f32_e32 v84, v84, v234
	ds_read_b128 v[196:199], v56 offset:24576
	ds_read_b128 v[200:203], v56 offset:25600
	ds_read_b128 v[204:207], v56 offset:26624
	ds_read_b128 v[208:211], v56 offset:27648
	s_waitcnt lgkmcnt(4)
	v_mul_f32_e32 v228, v29, v213
	v_mul_f32_e32 v229, v27, v215
	v_mul_f32_e32 v230, v33, v217
	v_mul_f32_e32 v231, v31, v219
	v_mul_f32_e32 v232, v41, v221
	v_mul_f32_e32 v233, v39, v223
	v_mul_f32_e32 v234, v37, v225
	v_mul_f32_e32 v235, v35, v227
	v_fmac_f32_e32 v228, v28, v212
	v_fmac_f32_e32 v229, v26, v214
	v_fmac_f32_e32 v230, v32, v216
	v_fmac_f32_e32 v231, v30, v218
	v_fmac_f32_e32 v232, v40, v220
	v_fmac_f32_e32 v233, v38, v222
	v_fmac_f32_e32 v234, v36, v224
	v_fmac_f32_e32 v235, v34, v226
	v_add_f32_e32 v228, v228, v229
	v_add_f32_e32 v230, v230, v231
	v_add_f32_e32 v232, v232, v233
	v_add_f32_e32 v234, v234, v235
	v_add_f32_e32 v85, 0, v228
	v_add_f32_e32 v85, v85, v230
	v_add_f32_e32 v85, v85, v232
	v_add_f32_e32 v85, v85, v234
	ds_read_b128 v[212:215], v56 offset:28672
	ds_read_b128 v[216:219], v56 offset:29696
	ds_read_b128 v[220:223], v56 offset:30720
	ds_read_b128 v[224:227], v56 offset:31744
	s_waitcnt lgkmcnt(4)
	v_mul_f32_e32 v228, v29, v197
	v_mul_f32_e32 v229, v27, v199
	v_mul_f32_e32 v230, v33, v201
	v_mul_f32_e32 v231, v31, v203
	v_mul_f32_e32 v232, v41, v205
	v_mul_f32_e32 v233, v39, v207
	v_mul_f32_e32 v234, v37, v209
	v_mul_f32_e32 v235, v35, v211
	v_fmac_f32_e32 v228, v28, v196
	v_fmac_f32_e32 v229, v26, v198
	v_fmac_f32_e32 v230, v32, v200
	v_fmac_f32_e32 v231, v30, v202
	v_fmac_f32_e32 v232, v40, v204
	v_fmac_f32_e32 v233, v38, v206
	v_fmac_f32_e32 v234, v36, v208
	v_fmac_f32_e32 v235, v34, v210
	v_add_f32_e32 v228, v228, v229
	v_add_f32_e32 v230, v230, v231
	v_add_f32_e32 v232, v232, v233
	v_add_f32_e32 v234, v234, v235
	v_add_f32_e32 v86, 0, v228
	v_add_f32_e32 v86, v86, v230
	v_add_f32_e32 v86, v86, v232
	v_add_f32_e32 v86, v86, v234
	ds_read_b128 v[196:199], v56 offset:32768
	ds_read_b128 v[200:203], v56 offset:33792
	ds_read_b128 v[204:207], v56 offset:34816
	ds_read_b128 v[208:211], v56 offset:35840
	s_waitcnt lgkmcnt(4)
	v_mul_f32_e32 v228, v29, v213
	v_mul_f32_e32 v229, v27, v215
	v_mul_f32_e32 v230, v33, v217
	v_mul_f32_e32 v231, v31, v219
	v_mul_f32_e32 v232, v41, v221
	v_mul_f32_e32 v233, v39, v223
	v_mul_f32_e32 v234, v37, v225
	v_mul_f32_e32 v235, v35, v227
	v_fmac_f32_e32 v228, v28, v212
	v_fmac_f32_e32 v229, v26, v214
	v_fmac_f32_e32 v230, v32, v216
	v_fmac_f32_e32 v231, v30, v218
	v_fmac_f32_e32 v232, v40, v220
	v_fmac_f32_e32 v233, v38, v222
	v_fmac_f32_e32 v234, v36, v224
	v_fmac_f32_e32 v235, v34, v226
	v_add_f32_e32 v228, v228, v229
	v_add_f32_e32 v230, v230, v231
	v_add_f32_e32 v232, v232, v233
	v_add_f32_e32 v234, v234, v235
	v_add_f32_e32 v87, 0, v228
	v_add_f32_e32 v87, v87, v230
	v_add_f32_e32 v87, v87, v232
	v_add_f32_e32 v87, v87, v234
	ds_read_b128 v[212:215], v56 offset:36864
	ds_read_b128 v[216:219], v56 offset:37888
	ds_read_b128 v[220:223], v56 offset:38912
	ds_read_b128 v[224:227], v56 offset:39936
	s_waitcnt lgkmcnt(4)
	v_mul_f32_e32 v228, v29, v197
	v_mul_f32_e32 v229, v27, v199
	v_mul_f32_e32 v230, v33, v201
	v_mul_f32_e32 v231, v31, v203
	v_mul_f32_e32 v232, v41, v205
	v_mul_f32_e32 v233, v39, v207
	v_mul_f32_e32 v234, v37, v209
	v_mul_f32_e32 v235, v35, v211
	v_fmac_f32_e32 v228, v28, v196
	v_fmac_f32_e32 v229, v26, v198
	v_fmac_f32_e32 v230, v32, v200
	v_fmac_f32_e32 v231, v30, v202
	v_fmac_f32_e32 v232, v40, v204
	v_fmac_f32_e32 v233, v38, v206
	v_fmac_f32_e32 v234, v36, v208
	v_fmac_f32_e32 v235, v34, v210
	v_add_f32_e32 v228, v228, v229
	v_add_f32_e32 v230, v230, v231
	v_add_f32_e32 v232, v232, v233
	v_add_f32_e32 v234, v234, v235
	v_add_f32_e32 v88, 0, v228
	v_add_f32_e32 v88, v88, v230
	v_add_f32_e32 v88, v88, v232
	v_add_f32_e32 v88, v88, v234
	ds_read_b128 v[196:199], v56 offset:40960
	ds_read_b128 v[200:203], v56 offset:41984
	ds_read_b128 v[204:207], v56 offset:43008
	ds_read_b128 v[208:211], v56 offset:44032
	s_waitcnt lgkmcnt(4)
	v_mul_f32_e32 v228, v29, v213
	v_mul_f32_e32 v229, v27, v215
	v_mul_f32_e32 v230, v33, v217
	v_mul_f32_e32 v231, v31, v219
	v_mul_f32_e32 v232, v41, v221
	v_mul_f32_e32 v233, v39, v223
	v_mul_f32_e32 v234, v37, v225
	v_mul_f32_e32 v235, v35, v227
	v_fmac_f32_e32 v228, v28, v212
	v_fmac_f32_e32 v229, v26, v214
	v_fmac_f32_e32 v230, v32, v216
	v_fmac_f32_e32 v231, v30, v218
	v_fmac_f32_e32 v232, v40, v220
	v_fmac_f32_e32 v233, v38, v222
	v_fmac_f32_e32 v234, v36, v224
	v_fmac_f32_e32 v235, v34, v226
	v_add_f32_e32 v228, v228, v229
	v_add_f32_e32 v230, v230, v231
	v_add_f32_e32 v232, v232, v233
	v_add_f32_e32 v234, v234, v235
	v_add_f32_e32 v89, 0, v228
	v_add_f32_e32 v89, v89, v230
	v_add_f32_e32 v89, v89, v232
	v_add_f32_e32 v89, v89, v234
	ds_read_b128 v[212:215], v56 offset:45056
	ds_read_b128 v[216:219], v56 offset:46080
	ds_read_b128 v[220:223], v56 offset:47104
	ds_read_b128 v[224:227], v56 offset:48128
	s_waitcnt lgkmcnt(4)
	v_mul_f32_e32 v228, v29, v197
	v_mul_f32_e32 v229, v27, v199
	v_mul_f32_e32 v230, v33, v201
	v_mul_f32_e32 v231, v31, v203
	v_mul_f32_e32 v232, v41, v205
	v_mul_f32_e32 v233, v39, v207
	v_mul_f32_e32 v234, v37, v209
	v_mul_f32_e32 v235, v35, v211
	v_fmac_f32_e32 v228, v28, v196
	v_fmac_f32_e32 v229, v26, v198
	v_fmac_f32_e32 v230, v32, v200
	v_fmac_f32_e32 v231, v30, v202
	v_fmac_f32_e32 v232, v40, v204
	v_fmac_f32_e32 v233, v38, v206
	v_fmac_f32_e32 v234, v36, v208
	v_fmac_f32_e32 v235, v34, v210
	v_add_f32_e32 v228, v228, v229
	v_add_f32_e32 v230, v230, v231
	v_add_f32_e32 v232, v232, v233
	v_add_f32_e32 v234, v234, v235
	v_add_f32_e32 v90, 0, v228
	v_add_f32_e32 v90, v90, v230
	v_add_f32_e32 v90, v90, v232
	v_add_f32_e32 v90, v90, v234
	ds_read_b128 v[196:199], v56 offset:49152
	ds_read_b128 v[200:203], v56 offset:50176
	ds_read_b128 v[204:207], v56 offset:51200
	ds_read_b128 v[208:211], v56 offset:52224
	s_waitcnt lgkmcnt(4)
	v_mul_f32_e32 v228, v29, v213
	v_mul_f32_e32 v229, v27, v215
	v_mul_f32_e32 v230, v33, v217
	v_mul_f32_e32 v231, v31, v219
	v_mul_f32_e32 v232, v41, v221
	v_mul_f32_e32 v233, v39, v223
	v_mul_f32_e32 v234, v37, v225
	v_mul_f32_e32 v235, v35, v227
	v_fmac_f32_e32 v228, v28, v212
	v_fmac_f32_e32 v229, v26, v214
	v_fmac_f32_e32 v230, v32, v216
	v_fmac_f32_e32 v231, v30, v218
	v_fmac_f32_e32 v232, v40, v220
	v_fmac_f32_e32 v233, v38, v222
	v_fmac_f32_e32 v234, v36, v224
	v_fmac_f32_e32 v235, v34, v226
	v_add_f32_e32 v228, v228, v229
	v_add_f32_e32 v230, v230, v231
	v_add_f32_e32 v232, v232, v233
	v_add_f32_e32 v234, v234, v235
	v_add_f32_e32 v91, 0, v228
	v_add_f32_e32 v91, v91, v230
	v_add_f32_e32 v91, v91, v232
	v_add_f32_e32 v91, v91, v234
	ds_read_b128 v[212:215], v56 offset:53248
	ds_read_b128 v[216:219], v56 offset:54272
	ds_read_b128 v[220:223], v56 offset:55296
	ds_read_b128 v[224:227], v56 offset:56320
	s_waitcnt lgkmcnt(4)
	v_mul_f32_e32 v228, v29, v197
	v_mul_f32_e32 v229, v27, v199
	v_mul_f32_e32 v230, v33, v201
	v_mul_f32_e32 v231, v31, v203
	v_mul_f32_e32 v232, v41, v205
	v_mul_f32_e32 v233, v39, v207
	v_mul_f32_e32 v234, v37, v209
	v_mul_f32_e32 v235, v35, v211
	v_fmac_f32_e32 v228, v28, v196
	v_fmac_f32_e32 v229, v26, v198
	v_fmac_f32_e32 v230, v32, v200
	v_fmac_f32_e32 v231, v30, v202
	v_fmac_f32_e32 v232, v40, v204
	v_fmac_f32_e32 v233, v38, v206
	v_fmac_f32_e32 v234, v36, v208
	v_fmac_f32_e32 v235, v34, v210
	v_add_f32_e32 v228, v228, v229
	v_add_f32_e32 v230, v230, v231
	v_add_f32_e32 v232, v232, v233
	v_add_f32_e32 v234, v234, v235
	v_add_f32_e32 v92, 0, v228
	v_add_f32_e32 v92, v92, v230
	v_add_f32_e32 v92, v92, v232
	v_add_f32_e32 v92, v92, v234
	ds_read_b128 v[196:199], v56 offset:57344
	ds_read_b128 v[200:203], v56 offset:58368
	ds_read_b128 v[204:207], v56 offset:59392
	ds_read_b128 v[208:211], v56 offset:60416
	s_waitcnt lgkmcnt(4)
	v_mul_f32_e32 v228, v29, v213
	v_mul_f32_e32 v229, v27, v215
	v_mul_f32_e32 v230, v33, v217
	v_mul_f32_e32 v231, v31, v219
	v_mul_f32_e32 v232, v41, v221
	v_mul_f32_e32 v233, v39, v223
	v_mul_f32_e32 v234, v37, v225
	v_mul_f32_e32 v235, v35, v227
	v_fmac_f32_e32 v228, v28, v212
	v_fmac_f32_e32 v229, v26, v214
	v_fmac_f32_e32 v230, v32, v216
	v_fmac_f32_e32 v231, v30, v218
	v_fmac_f32_e32 v232, v40, v220
	v_fmac_f32_e32 v233, v38, v222
	v_fmac_f32_e32 v234, v36, v224
	v_fmac_f32_e32 v235, v34, v226
	v_add_f32_e32 v228, v228, v229
	v_add_f32_e32 v230, v230, v231
	v_add_f32_e32 v232, v232, v233
	v_add_f32_e32 v234, v234, v235
	v_add_f32_e32 v93, 0, v228
	v_add_f32_e32 v93, v93, v230
	v_add_f32_e32 v93, v93, v232
	v_add_f32_e32 v93, v93, v234
	ds_read_b128 v[212:215], v56 offset:61440
	ds_read_b128 v[216:219], v56 offset:62464
	ds_read_b128 v[220:223], v56 offset:63488
	ds_read_b128 v[224:227], v56 offset:64512
	s_waitcnt lgkmcnt(4)
	v_mul_f32_e32 v228, v29, v197
	v_mul_f32_e32 v229, v27, v199
	v_mul_f32_e32 v230, v33, v201
	v_mul_f32_e32 v231, v31, v203
	v_mul_f32_e32 v232, v41, v205
	v_mul_f32_e32 v233, v39, v207
	v_mul_f32_e32 v234, v37, v209
	v_mul_f32_e32 v235, v35, v211
	v_fmac_f32_e32 v228, v28, v196
	v_fmac_f32_e32 v229, v26, v198
	v_fmac_f32_e32 v230, v32, v200
	v_fmac_f32_e32 v231, v30, v202
	v_fmac_f32_e32 v232, v40, v204
	v_fmac_f32_e32 v233, v38, v206
	v_fmac_f32_e32 v234, v36, v208
	v_fmac_f32_e32 v235, v34, v210
	v_add_f32_e32 v228, v228, v229
	v_add_f32_e32 v230, v230, v231
	v_add_f32_e32 v232, v232, v233
	v_add_f32_e32 v234, v234, v235
	v_add_f32_e32 v94, 0, v228
	v_add_f32_e32 v94, v94, v230
	v_add_f32_e32 v94, v94, v232
	v_add_f32_e32 v94, v94, v234
	s_waitcnt lgkmcnt(0)
	v_mul_f32_e32 v228, v29, v213
	v_mul_f32_e32 v229, v27, v215
	v_mul_f32_e32 v230, v33, v217
	v_mul_f32_e32 v231, v31, v219
	v_mul_f32_e32 v232, v41, v221
	v_mul_f32_e32 v233, v39, v223
	v_mul_f32_e32 v234, v37, v225
	v_mul_f32_e32 v235, v35, v227
	v_fmac_f32_e32 v228, v28, v212
	v_fmac_f32_e32 v229, v26, v214
	v_fmac_f32_e32 v230, v32, v216
	v_fmac_f32_e32 v231, v30, v218
	v_fmac_f32_e32 v232, v40, v220
	v_fmac_f32_e32 v233, v38, v222
	v_fmac_f32_e32 v234, v36, v224
	v_fmac_f32_e32 v235, v34, v226
	v_add_f32_e32 v228, v228, v229
	v_add_f32_e32 v230, v230, v231
	v_add_f32_e32 v232, v232, v233
	v_add_f32_e32 v234, v234, v235
	v_add_f32_e32 v95, 0, v228
	v_add_f32_e32 v95, v95, v230
	v_add_f32_e32 v95, v95, v232
	v_add_f32_e32 v95, v95, v234
	v_permlane32_swap_b32_e32 v80, v88
	v_permlane32_swap_b32_e32 v81, v89
	v_permlane32_swap_b32_e32 v82, v90
	v_permlane32_swap_b32_e32 v83, v91
	v_permlane32_swap_b32_e32 v84, v92
	v_permlane32_swap_b32_e32 v85, v93
	v_permlane32_swap_b32_e32 v86, v94
	v_permlane32_swap_b32_e32 v87, v95
	v_add_f32_e32 v80, v80, v88
	v_add_f32_e32 v81, v81, v89
	v_add_f32_e32 v82, v82, v90
	v_add_f32_e32 v83, v83, v91
	v_add_f32_e32 v84, v84, v92
	v_add_f32_e32 v85, v85, v93
	v_add_f32_e32 v86, v86, v94
	v_add_f32_e32 v87, v87, v95
	s_mov_b32 vcc_lo, 0xffff0000
	s_mov_b32 vcc_hi, 0xffff0000
	v_cndmask_b32_e32 v240, v84, v80, vcc
	v_cndmask_b32_e32 v241, v85, v81, vcc
	v_cndmask_b32_e32 v242, v86, v82, vcc
	v_cndmask_b32_e32 v243, v87, v83, vcc
	v_cndmask_b32_e32 v236, v80, v84, vcc
	v_cndmask_b32_e32 v237, v81, v85, vcc
	v_cndmask_b32_e32 v238, v82, v86, vcc
	v_cndmask_b32_e32 v239, v83, v87, vcc
	ds_swizzle_b32 v232, v240 offset:swizzle(SWAP,16)
	ds_swizzle_b32 v233, v241 offset:swizzle(SWAP,16)
	ds_swizzle_b32 v234, v242 offset:swizzle(SWAP,16)
	ds_swizzle_b32 v235, v243 offset:swizzle(SWAP,16)
	s_waitcnt lgkmcnt(0)
	v_add_f32_e32 v88, v236, v232
	v_add_f32_e32 v89, v237, v233
	v_add_f32_e32 v90, v238, v234
	v_add_f32_e32 v91, v239, v235
	v_add_f32_dpp v88, v88, v88 row_ror:8 row_mask:0xf bank_mask:0xf
	v_add_f32_dpp v89, v89, v89 row_ror:8 row_mask:0xf bank_mask:0xf
	v_add_f32_dpp v90, v90, v90 row_ror:8 row_mask:0xf bank_mask:0xf
	v_add_f32_dpp v91, v91, v91 row_ror:8 row_mask:0xf bank_mask:0xf
	v_add_f32_dpp v88, v88, v88 row_ror:4 row_mask:0xf bank_mask:0xf
	v_add_f32_dpp v89, v89, v89 row_ror:4 row_mask:0xf bank_mask:0xf
	v_add_f32_dpp v90, v90, v90 row_ror:4 row_mask:0xf bank_mask:0xf
	v_add_f32_dpp v91, v91, v91 row_ror:4 row_mask:0xf bank_mask:0xf
	v_add_f32_dpp v88, v88, v88 quad_perm:[2,3,0,1] row_mask:0xf bank_mask:0xf
	v_add_f32_dpp v89, v89, v89 quad_perm:[2,3,0,1] row_mask:0xf bank_mask:0xf
	v_add_f32_dpp v90, v90, v90 quad_perm:[2,3,0,1] row_mask:0xf bank_mask:0xf
	v_add_f32_dpp v91, v91, v91 quad_perm:[2,3,0,1] row_mask:0xf bank_mask:0xf
	v_add_f32_dpp v88, v88, v88 quad_perm:[1,0,3,2] row_mask:0xf bank_mask:0xf
	v_add_f32_dpp v89, v89, v89 quad_perm:[1,0,3,2] row_mask:0xf bank_mask:0xf
	v_add_f32_dpp v90, v90, v90 quad_perm:[1,0,3,2] row_mask:0xf bank_mask:0xf
	v_add_f32_dpp v91, v91, v91 quad_perm:[1,0,3,2] row_mask:0xf bank_mask:0xf
	s_mov_b32 vcc_lo, 0xaaaaaaaa
	s_mov_b32 vcc_hi, 0xaaaaaaaa
	v_cndmask_b32_e32 v92, v88, v89, vcc
	v_cndmask_b32_e32 v93, v90, v91, vcc
	s_mov_b32 vcc_lo, 0xcccccccc
	s_mov_b32 vcc_hi, 0xcccccccc
	v_cndmask_b32_e32 v92, v92, v93, vcc
	ds_bpermute_b32 v26, v97, v92
	s_waitcnt lgkmcnt(0)
	s_and_saveexec_b64 s[0:1], s[4:5]
	s_cbranch_execz .LBB0_693
	s_mov_b32 s2, 0xbfb8aa3b
	v_add_f32_e32 v26, v26, v99
	v_mul_f32_e64 v27, |v26|, s2
	v_exp_f32_e32 v27, v27
	v_min_f32_e32 v26, 0, v26
	v_add_f32_e32 v27, 1.0, v27
	v_log_f32_e32 v27, v27
	s_nop 0
	v_fmac_f32_e32 v26, 0xbf317218, v27
	global_store_dword v[16:17], v26, off
	s_branch .LBB0_693

.Lmy_nm_noreload:
	v_mul_f32_e32 v0, v31, v31
	v_mul_f32_e32 v60, v33, v33
	v_mul_f32_e32 v61, v11, v11
	v_mul_f32_e32 v62, v13, v13
	v_mul_f32_e32 v63, v7, v7
	v_mul_f32_e32 v64, v9, v9
	v_fmac_f32_e32 v0, v30, v30
	v_fmac_f32_e32 v60, v32, v32
	v_fmac_f32_e32 v61, v10, v10
	v_fmac_f32_e32 v62, v12, v12
	v_mul_f32_e32 v65, v3, v3
	v_mul_f32_e32 v66, v5, v5
	v_fmac_f32_e32 v63, v6, v6
	v_fmac_f32_e32 v64, v8, v8
	v_add_f32_e32 v0, v0, v60
	v_add_f32_e32 v60, v61, v62
	v_fmac_f32_e32 v65, v2, v2
	v_fmac_f32_e32 v66, v4, v4
	v_add_f32_e32 v61, v63, v64
	v_add_f32_e32 v0, v0, v60
	v_add_f32_e32 v62, v65, v66
	v_add_f32_e32 v0, v61, v0
	v_add_f32_e32 v0, v62, v0
	s_and_b64 vcc, exec, s[4:5]
	s_mov_b32 s6, s2
	s_waitcnt lgkmcnt(0)
	s_nop 1
	v_add_f32_dpp v0, v0, v0 quad_perm:[1,0,3,2] row_mask:0xf bank_mask:0xf
	s_waitcnt lgkmcnt(0)
	s_nop 1
	v_add_f32_dpp v0, v0, v0 quad_perm:[2,3,0,1] row_mask:0xf bank_mask:0xf
	s_waitcnt lgkmcnt(0)
	s_nop 1
	v_add_f32_dpp v0, v0, v0 row_half_mirror row_mask:0xf bank_mask:0xf
	s_waitcnt lgkmcnt(0)
	s_nop 1
	v_add_f32_dpp v0, v0, v0 row_mirror row_mask:0xf bank_mask:0xf
	v_mov_b32_e32 v60, v0
	s_nop 1
	v_permlane16_swap_b32_e32 v60, v0
	s_waitcnt lgkmcnt(0)
	v_add_f32_e32 v0, v0, v60
	v_mov_b32_e32 v60, v0
	s_nop 1
	v_permlane32_swap_b32_e32 v0, v60
	v_add_f32_e32 v0, v0, v60
	v_fmamk_f32 v0, v0, 0x3a800000, v244
	v_rsq_f32_e32 v0, v0
	s_nop 0
	v_pk_mul_f32 v[32:33], v[32:33], v[0:1] op_sel_hi:[1,0]
	v_pk_mul_f32 v[30:31], v[30:31], v[0:1] op_sel_hi:[1,0]
	v_pk_mul_f32 v[12:13], v[12:13], v[0:1] op_sel_hi:[1,0]
	v_pk_mul_f32 v[10:11], v[10:11], v[0:1] op_sel_hi:[1,0]
	v_pk_mul_f32 v[8:9], v[8:9], v[0:1] op_sel_hi:[1,0]
	v_pk_mul_f32 v[6:7], v[6:7], v[0:1] op_sel_hi:[1,0]
	v_mov_b64_e32 v[44:45], v[116:117]
	v_mov_b64_e32 v[46:47], v[118:119]
	v_pk_mul_f32 v[30:31], v[44:45], v[30:31]
	v_pk_mul_f32 v[32:33], v[46:47], v[32:33]
	v_mov_b64_e32 v[48:49], v[120:121]
	v_mov_b64_e32 v[50:51], v[122:123]
	v_pk_add_f32 v[46:47], v[48:49], 1.0 op_sel_hi:[1,0]
	v_pk_add_f32 v[44:45], v[50:51], 1.0 op_sel_hi:[1,0]
	v_mov_b64_e32 v[52:53], v[124:125]
	v_mov_b64_e32 v[54:55], v[126:127]
	v_pk_fma_f32 v[30:31], v[46:47], v[30:31], v[52:53]
	v_pk_fma_f32 v[32:33], v[44:45], v[32:33], v[54:55]
	v_cvt_pk_bf16_f32 v30, v30, v31
	s_nop 0
	v_cvt_pk_bf16_f32 v31, v32, v33
	global_store_dwordx2 v[42:43], v[30:31], off
	v_mov_b64_e32 v[30:31], v[80:81]
	v_mov_b64_e32 v[32:33], v[82:83]
	v_mov_b64_e32 v[44:45], v[84:85]
	v_mov_b64_e32 v[46:47], v[86:87]
	v_mov_b64_e32 v[48:49], v[88:89]
	v_mov_b64_e32 v[50:51], v[90:91]
	v_pk_mul_f32 v[10:11], v[30:31], v[10:11]
	v_pk_mul_f32 v[12:13], v[32:33], v[12:13]
	v_pk_add_f32 v[32:33], v[44:45], 1.0 op_sel_hi:[1,0]
	v_pk_add_f32 v[30:31], v[46:47], 1.0 op_sel_hi:[1,0]
	v_pk_fma_f32 v[10:11], v[32:33], v[10:11], v[48:49]
	v_pk_fma_f32 v[12:13], v[30:31], v[12:13], v[50:51]
	v_cvt_pk_bf16_f32 v10, v10, v11
	s_nop 0
	v_cvt_pk_bf16_f32 v11, v12, v13
	global_store_dwordx2 v[42:43], v[10:11], off offset:512
	s_waitcnt vmcnt(2)
	v_mov_b64_e32 v[10:11], v[92:93]
	v_mov_b64_e32 v[12:13], v[94:95]
	v_mov_b64_e32 v[30:31], v[96:97]
	v_mov_b64_e32 v[32:33], v[98:99]
	v_mov_b64_e32 v[44:45], v[100:101]
	v_mov_b64_e32 v[46:47], v[102:103]
	v_pk_mul_f32 v[6:7], v[6:7], v[10:11]
	v_pk_mul_f32 v[8:9], v[8:9], v[12:13]
	v_pk_add_f32 v[12:13], v[30:31], 1.0 op_sel_hi:[1,0]
	v_pk_add_f32 v[10:11], v[32:33], 1.0 op_sel_hi:[1,0]
	v_pk_fma_f32 v[6:7], v[6:7], v[12:13], v[44:45]
	v_pk_fma_f32 v[8:9], v[8:9], v[10:11], v[46:47]
	v_cvt_pk_bf16_f32 v6, v6, v7
	v_mov_b32_e32 v30, v14
	v_cvt_pk_bf16_f32 v7, v8, v9
	global_store_dwordx2 v[42:43], v[6:7], off offset:1024
	v_mov_b64_e32 v[44:45], v[104:105]
	v_mov_b64_e32 v[46:47], v[106:107]
	v_mov_b64_e32 v[48:49], v[108:109]
	v_mov_b64_e32 v[50:51], v[110:111]
	v_mov_b64_e32 v[52:53], v[112:113]
	v_mov_b64_e32 v[54:55], v[114:115]
	v_pk_mul_f32 v[58:59], v[2:3], v[0:1] op_sel_hi:[1,0]
	v_pk_mul_f32 v[56:57], v[4:5], v[0:1] op_sel_hi:[1,0]
	v_mov_b32_e32 v31, v15
	v_mov_b32_e32 v12, v20
	v_mov_b32_e32 v13, v21
	v_mov_b32_e32 v32, v16
	v_mov_b32_e32 v33, v17
	v_mov_b32_e32 v10, v18
	v_mov_b32_e32 v11, v19
	v_mov_b32_e32 v6, v22
	v_mov_b32_e32 v7, v23
	v_mov_b32_e32 v8, v24
	v_mov_b32_e32 v9, v25
	v_mov_b32_e32 v2, v26
	v_mov_b32_e32 v3, v27
	v_mov_b32_e32 v4, v28
	v_mov_b32_e32 v5, v29
	v_pk_mul_f32 v[14:15], v[58:59], v[44:45]
	v_pk_add_f32 v[20:21], v[48:49], 1.0 op_sel_hi:[1,0]
	v_pk_mul_f32 v[16:17], v[56:57], v[46:47]
	v_pk_add_f32 v[18:19], v[50:51], 1.0 op_sel_hi:[1,0]
	v_pk_fma_f32 v[14:15], v[14:15], v[20:21], v[52:53]
	v_pk_fma_f32 v[16:17], v[16:17], v[18:19], v[54:55]
	v_cvt_pk_bf16_f32 v14, v14, v15
	s_nop 0
	v_cvt_pk_bf16_f32 v15, v16, v17
	global_store_dwordx2 v[42:43], v[14:15], off offset:1536
	v_lshl_add_u64 v[42:43], v[42:43], 0, s[0:1]
	s_cbranch_vccnz .LBB0_707
